# ffn_up K-loop: direct global-to-LDS loads (global_load_lds, source-swizzled) replace register staging + ds_write, 2 slots distance 1
# speedup vs baseline: 1.0160x; 1.0077x over previous
; #define LAS __attribute__((address_space(3)))
; DI unsigned xb_add(unsigned* p, unsigned v) { return __hip_atomic_fetch_add(p, v, __ATOMIC_RELAXED, __HIP_MEMORY_SCOPE_AGENT); }
; DI unsigned xb_xcc_id() { return (unsigned)__builtin_amdgcn_s_getreg((3 << 11) | 20) & 0xFu; }
; DI XcdBarrier xcd_barrier_post(unsigned* bar, volatile LAS unsigned* st) {
;   XcdBarrier b; b.bar = bar; b.x = xb_xcc_id(); b.st = st;
;   if (threadIdx.x == 0) (void)xb_add(&bar[XB_XCNT(b.x)], 1u);
;   return b;
; }
; __global__ void __launch_bounds__(NTHREADS) fwd_kernel(P p) {
;   extern __shared__ __attribute__((aligned(16))) char lds_raw[];
;   char* lds = lds_raw + LDS_FRONT;
;   cg::grid_group grid = cg::this_grid();
;   if (threadIdx.x == 0) *(u32x4*)lds_raw = u32x4{0u, 0u, 0u, 0u};
;   __syncthreads();
;   (void)xcd_barrier_post((unsigned*)(p.ws + OFF_BAR), (volatile LAS unsigned*)lds_raw);
_Z10fwd_kernel1P:
	v_readfirstlane_b32 s98, v0
	s_nop 3
	s_bfe_u32 s98, s98, 0x30006
	s_lshl_b32 s98, s98, 10
	s_add_u32 s98, s98, 0x900
	s_load_dwordx2 s[64:65], s[0:1], 0x110
	s_load_dwordx4 s[60:63], s[0:1], 0x100
	s_add_u32 s14, s0, 0x118
	s_mov_b32 s94, s2
	s_addc_u32 s15, s1, 0
	v_and_b32_e32 v198, 0x3ff, v0
	v_cmp_eq_u32_e64 s[2:3], 0, v198
	s_mov_b64 s[4:5], exec
	s_nop 0
	v_writelane_b32 v252, s2, 0
	s_nop 1
	v_writelane_b32 v252, s3, 1
	s_and_b64 s[2:3], s[4:5], s[2:3]
	s_mov_b64 exec, s[2:3]
	v_mov_b32_e32 v2, 0
	v_mov_b32_e32 v3, v2
	v_mov_b32_e32 v4, v2
	v_mov_b32_e32 v5, v2
	ds_write_b128 v2, v[2:5]
	s_or_b64 exec, exec, s[4:5]
	s_load_dwordx2 s[66:67], s[0:1], 0x118
	s_load_dword s2, s[0:1], 0x120
	s_waitcnt lgkmcnt(0)
	s_add_u32 s4, s64, 0x384a2000
	s_addc_u32 s5, s65, 0
	v_writelane_b32 v252, s4, 2
	s_barrier
	s_nop 0
	v_writelane_b32 v252, s5, 3
	s_getreg_b32 s3, hwreg(HW_REG_XCC_ID, 0, 4)
	s_mov_b64 s[4:5], exec
	v_readlane_b32 s6, v252, 0
	v_readlane_b32 s7, v252, 1
	s_and_b64 s[6:7], s[4:5], s[6:7]
	s_mov_b64 exec, s[6:7]
	s_cbranch_execz .LBB0_5
	s_mov_b64 s[6:7], exec
	v_mbcnt_lo_u32_b32 v1, s6, 0
	v_mbcnt_hi_u32_b32 v1, s7, v1
	v_cmp_eq_u32_e32 vcc, 0, v1
	s_and_b64 s[8:9], exec, vcc
	s_mov_b64 exec, s[8:9]
	s_cbranch_execz .LBB0_5
	s_lshl_b32 s3, s3, 8
	s_bcnt1_i32_b64 s6, s[6:7]
	s_and_b32 s3, s3, 0xf00
	v_mov_b32_e32 v2, s6
	v_readlane_b32 s6, v252, 2
	v_mov_b32_e32 v1, s3
	v_readlane_b32 s7, v252, 3
	s_nop 4
	global_atomic_add v1, v2, s[6:7] offset:1024

; template <bool SW, class AL, class BL>
; DI void gemm_run16(int tid, char* lds, const AL& al, const BL& bl, int nk, f32x4 (&acc)[4][4], u32x4 (&ra0)[4], u32x4 (&rb0)[2], u32x4 (&ra1)[4], u32x4 (&rb1)[2]) {
;     ...
;   const int lane = tid & 63, wid = tid >> 6, l15 = lane & 15, g = lane >> 4;
;   const int wm = wid >> 1, wn = wid & 1, lr = tid >> 3, lc = tid & 7;
;   char* const wa = lds + lr * RB_ + ((lc ^ ((lr >> 1) & 7)) << 4);
;   const int o0 = (g ^ ((lane >> 1) & 7)) << 4, o1 = o0 ^ 64;
;   const int aoff = (wm * 64 + l15) * RB_, boff = AB + (wn * 64 + l15) * RB_;
; static __device__ __forceinline__ void phase_ffn_up(const P& p, int l, char* lds) {
;     ...
;   auto mk = [&](int rt_, int nt_, LdRows& a_, LdRows& b_) {
;     const int ts_ = 254 * rt_ - 1;
; #pragma unroll
;     for (int j = 0; j < 4; ++j) { const int tt = ts_ + lr + 64 * j; a_.p[j] = (tt >= 0 && tt < MTOT) ? H + (size_t)tt * 1024 : (const u16*)(p.ws + OFF_ZERO); }
; #pragma unroll
;     for (int j = 0; j < 2; ++j) b_.p[j] = W + (size_t)(nt_ * 128 + lr + 64 * j) * 1024;
;     b_.p[2] = b_.p[3] = b_.p[0];
;   };
;   int s = tile_next(0, ns, RT, 44, 8, 4, rt, nt);
;   if (s >= 0) { mk(rt, nt, al, bl); gemm_issue<4, 2>(tid, al, bl, 16, ra0, rb0, ra1, rb1); }
.LBB0_1057:
	v_ashrrev_i32_e32 v135, 3, v50
	s_mul_i32 s4, s31, 0xfe
	v_add_u32_e32 v140, -1, v135
	v_add_u32_e32 v4, s4, v140
	v_readlane_b32 s4, v254, 20
	v_lshlrev_b32_e32 v0, 11, v4
	s_mov_b32 s5, 0x10800
	v_mov_b32_e32 v5, s4
	v_readlane_b32 s4, v254, 19
	v_lshl_add_u64 v[2:3], s[60:61], 0, v[0:1]
	v_cmp_gt_u32_e32 vcc, s5, v4
	v_mov_b32_e32 v6, s4
	v_add_u32_e32 v7, 64, v4
	v_cndmask_b32_e32 v119, v5, v3, vcc
	v_cndmask_b32_e32 v118, v6, v2, vcc
	v_lshlrev_b32_e32 v0, 11, v7
	v_cmp_gt_u32_e32 vcc, s5, v7
	v_add_u32_e32 v7, 0x80, v4
	v_lshl_add_u64 v[2:3], s[60:61], 0, v[0:1]
	v_lshlrev_b32_e32 v0, 11, v7
	v_add_u32_e32 v4, 0xc0, v4
	v_cndmask_b32_e32 v121, v5, v3, vcc
	v_cndmask_b32_e32 v120, v6, v2, vcc
	v_lshl_add_u64 v[2:3], s[60:61], 0, v[0:1]
	v_cmp_gt_u32_e32 vcc, s5, v7
	v_lshlrev_b32_e32 v0, 11, v4
	v_readlane_b32 s0, v254, 62
	v_cndmask_b32_e32 v125, v5, v3, vcc
	v_cndmask_b32_e32 v124, v6, v2, vcc
	v_lshl_add_u64 v[2:3], s[60:61], 0, v[0:1]
	v_cmp_gt_u32_e32 vcc, s5, v4
	s_add_u32 s0, s0, 0x1958000
	v_readlane_b32 s1, v254, 63
	v_cndmask_b32_e32 v126, v6, v2, vcc
	v_lshl_add_u32 v2, s33, 7, v135
	v_cndmask_b32_e32 v127, v5, v3, vcc
	v_ashrrev_i32_e32 v3, 31, v2
	v_lshlrev_b64 v[4:5], 11, v[2:3]
	v_add_u32_e32 v2, 64, v2
	v_ashrrev_i32_e32 v3, 31, v2
	s_addc_u32 s1, s1, 0
	v_lshlrev_b64 v[2:3], 11, v[2:3]
	v_lshlrev_b32_e32 v0, 4, v50
	v_lshl_add_u64 v[128:129], s[0:1], 0, v[4:5]
	v_lshl_add_u64 v[130:131], s[0:1], 0, v[2:3]
	v_and_b32_e32 v122, 0x70, v0
	v_mov_b32_e32 v123, v1
	v_lshl_add_u64 v[2:3], v[118:119], 0, v[122:123]
	v_lshl_add_u64 v[4:5], v[120:121], 0, v[122:123]
	v_lshl_add_u64 v[6:7], v[124:125], 0, v[122:123]
	v_lshl_add_u64 v[8:9], v[126:127], 0, v[122:123]
	s_waitcnt vmcnt(0)
	v_lshl_add_u64 v[10:11], v[128:129], 0, v[122:123]
	v_lshl_add_u64 v[12:13], v[130:131], 0, v[122:123]
	global_load_dwordx4 v[26:29], v[2:3], off
	global_load_dwordx4 v[14:17], v[2:3], off offset:128
	global_load_dwordx4 v[30:33], v[4:5], off
	global_load_dwordx4 v[18:21], v[4:5], off offset:128
	global_load_dwordx4 v[34:37], v[6:7], off
	global_load_dwordx4 v[22:25], v[6:7], off offset:128
	global_load_dwordx4 v[38:41], v[8:9], off
	s_nop 0
	global_load_dwordx4 v[2:5], v[8:9], off offset:128
	global_load_dwordx4 v[42:45], v[10:11], off
	s_nop 0
	global_load_dwordx4 v[6:9], v[10:11], off offset:128
	global_load_dwordx4 v[46:49], v[12:13], off
	s_nop 0
	global_load_dwordx4 v[10:13], v[12:13], off offset:128
	v_readlane_b32 s8, v252, 37
	s_mul_i32 s5, s53, 0x10800
	v_readlane_b32 s12, v252, 41
	v_readlane_b32 s20, v252, 49
	s_mul_hi_u32 s4, s53, 0x10800
	v_readlane_b32 s13, v252, 42
	v_readlane_b32 s21, v252, 50
	s_add_u32 s12, s20, s5
	v_readlane_b32 s16, v252, 45
	v_readlane_b32 s22, v252, 51
	s_addc_u32 s13, s21, s4
	s_mul_i32 s5, s53, 0x5800
	v_readlane_b32 s17, v252, 46
	v_readlane_b32 s23, v252, 52
	s_mul_hi_u32 s4, s53, 0x5800
	s_add_u32 s16, s22, s5
	s_addc_u32 s17, s23, s4
	s_movk_i32 s4, 0x70
	v_and_b32_e32 v52, 0xffffff80, v0
	v_bitop3_b32 v0, v0, s4, v50 bitop3:0x48
	v_add3_u32 v141, 0, v52, v0
	v_and_b32_e32 v251, 0x70, v141
	v_lshlrev_b32_e32 v0, 3, v50
	v_and_b32_e32 v52, 48, v50
	v_lshlrev_b32_e32 v56, 2, v50
	v_and_b32_e32 v51, 15, v50
	v_bitop3_b32 v142, v0, v52, s4 bitop3:0x6c
	v_ashrrev_i32_e32 v53, 1, v50
	s_movk_i32 s4, 0xffc0
	v_and_b32_e32 v56, 0x100, v56
	v_and_b32_e32 v0, 24, v0
	v_and_or_b32 v51, v53, s4, v51
	v_lshlrev_b32_e32 v53, 7, v50
	v_add3_u32 v52, 0, v52, v56
	v_bfe_u32 v50, v50, 2, 1
	v_lshlrev_b32_e32 v56, 2, v0
	s_movk_i32 s6, 0x210
	v_readlane_b32 s10, v252, 39
	v_and_b32_e32 v53, 0x2780, v53
	v_xor_b32_e32 v143, 64, v142
	v_readlane_b32 s4, v254, 28
	v_lshl_or_b32 v150, v50, 8, v56
	v_mul_lo_u32 v56, v135, s6
	v_readlane_b32 s9, v252, 38
	v_or_b32_e32 v54, 0x8000, v53
	v_add_u32_e32 v144, 0, v53
	v_add_u32_e32 v53, s4, v142
	v_add_u32_e32 v55, s4, v143
	s_add_i32 s4, s25, 7
	s_movk_i32 s10, 0xfe
	v_add_u32_e32 v151, 0, v56
	v_add_u32_e32 v56, 63, v135
	v_add_u32_e32 v57, 0x7f, v135
	v_readlane_b32 s11, v252, 40
	v_lshl_add_u32 v145, v51, 7, 0
	s_lshr_b32 s30, s4, 3
	v_mul_lo_u32 v51, v51, s6
	v_cmp_gt_u32_e64 s[6:7], s10, v56
	v_add_u32_e32 v56, 0x8400, v151
	v_cmp_gt_u32_e64 s[8:9], s10, v57
	v_add_u32_e32 v57, 0x10800, v151
	v_add_u32_e32 v58, 0xbf, v135
	v_add_u32_e32 v146, 0x10900, v141
	v_add_u32_e32 v147, 0x12900, v141
	v_add_u32_e32 v148, 0x14900, v141
	v_add_u32_e32 v149, 0x16900, v141
	s_mul_i32 s30, s30, 11
	v_cmp_gt_u32_e64 s[4:5], s10, v140
	v_cmp_gt_u32_e64 s[10:11], s10, v58
	v_lshl_or_b32 v152, v50, 5, v0
	v_add_u32_e32 v153, v53, v54
	v_add_u32_e32 v154, v55, v54
	v_add_u32_e32 v155, v52, v51
	v_add_u32_e32 v156, v56, v150
	v_add_u32_e32 v157, v57, v150
	v_readlane_b32 s14, v252, 43
	v_readlane_b32 s15, v252, 44
	v_readlane_b32 s18, v252, 47
	v_readlane_b32 s19, v252, 48
	s_branch .LBB0_1059

; #define GLOAD(RA, RB, KT) do { const int kc_ = (KT) * 8 + lc; _Pragma("unroll") for (int j = 0; j < NA; ++j) RA[j] = al.load(j, kc_); _Pragma("unroll") for (int j = 0; j < NB; ++j) RB[j] = bl.load(j, kc_); } while (0)
; #define LWRITE(RA, RB, BUF) do { char* w_ = wa + (BUF) * STAGE; _Pragma("unroll") for (int j = 0; j < NA; ++j) *(u32x4*)(w_ + j * 64 * PITCH) = RA[j]; _Pragma("unroll") for (int j = 0; j < NB; ++j) *(u32x4*)(w_ + AB + j * 64 * PITCH) = RB[j]; } while (0)
; #define GLOAD(RA, RB, KT) do { const int kc_ = (KT) * 8 + lc; _Pragma("unroll") for (int j = 0; j < NA; ++j) RA[j] = al.load(j, kc_); _Pragma("unroll") for (int j = 0; j < NB; ++j) RB[j] = bl.load(j, kc_); } while (0)
; #define LWRITE(RA, RB, BUF) do { char* w_ = wa + (BUF) * STAGE; _Pragma("unroll") for (int j = 0; j < NA; ++j) *(u32x4*)(w_ + j * 64 * RB_) = RA[j]; _Pragma("unroll") for (int j = 0; j < NB; ++j) *(u32x4*)(w_ + AB + j * 64 * RB_) = RB[j]; } while (0)
; #define COMPUTE(BUF, RA, RB, WBUF) do { const char* sb = lds + (BUF) * STAGE; char* w_ = wa + (WBUF) * STAGE; \
;     KSTEP(o0); *(u32x4*)(w_) = RA[0]; *(u32x4*)(w_ + 64 * RB_) = RA[1]; *(u32x4*)(w_ + 128 * RB_) = RA[2]; \
;     KSTEP(o1); *(u32x4*)(w_ + 192 * RB_) = RA[3]; *(u32x4*)(w_ + AB) = RB[0]; *(u32x4*)(w_ + AB + 64 * RB_) = RB[1]; } while (0)
; template <bool SW, class AL, class BL>
; DI void gemm_run16(int tid, char* lds, const AL& al, const BL& bl, int nk, f32x4 (&acc)[4][4], u32x4 (&ra0)[4], u32x4 (&rb0)[2], u32x4 (&ra1)[4], u32x4 (&rb1)[2]) {
;     ...
;   const int kl = nk - 1;
;   LWRITE(ra0, rb0, 0);
;   __syncthreads();
; #pragma unroll 1
;   for (int kt = 0; kt < nk; kt += 2) {
;     GLOAD(ra0, rb0, (kt + 2 < kl ? kt + 2 : kl));
;     COMPUTE(0, ra1, rb1, 1);
;     __syncthreads();
;     if (kt + 1 >= nk) break;
;     GLOAD(ra1, rb1, (kt + 3 < kl ? kt + 3 : kl));
;     COMPUTE(1, ra0, rb0, 0);
;     __syncthreads();
.LBB0_1059:
	v_mov_b32_e32 v50, 0
	s_mov_b32 s34, s31
	s_mov_b32 s35, s33
	s_mov_b32 s18, -2
	v_mov_b32_e32 v51, v50
	v_mov_b32_e32 v52, v50
	v_mov_b32_e32 v53, v50
	v_mov_b32_e32 v54, v50
	v_mov_b32_e32 v55, v50
	v_mov_b32_e32 v56, v50
	v_mov_b32_e32 v57, v50
	v_mov_b32_e32 v58, v50
	v_mov_b32_e32 v59, v50
	v_mov_b32_e32 v60, v50
	v_mov_b32_e32 v61, v50
	v_mov_b32_e32 v62, v50
	v_mov_b32_e32 v63, v50
	v_mov_b32_e32 v64, v50
	v_mov_b32_e32 v65, v50
	v_mov_b32_e32 v66, v50
	v_mov_b32_e32 v67, v50
	v_mov_b32_e32 v68, v50
	v_mov_b32_e32 v69, v50
	v_mov_b32_e32 v70, v50
	v_mov_b32_e32 v71, v50
	v_mov_b32_e32 v72, v50
	v_mov_b32_e32 v73, v50
	v_mov_b32_e32 v74, v50
	v_mov_b32_e32 v75, v50
	v_mov_b32_e32 v76, v50
	v_mov_b32_e32 v77, v50
	v_mov_b32_e32 v78, v50
	v_mov_b32_e32 v79, v50
	v_mov_b32_e32 v80, v50
	v_mov_b32_e32 v81, v50
	v_mov_b32_e32 v82, v50
	v_mov_b32_e32 v83, v50
	v_mov_b32_e32 v84, v50
	v_mov_b32_e32 v85, v50
	v_mov_b32_e32 v86, v50
	v_mov_b32_e32 v87, v50
	v_mov_b32_e32 v88, v50
	v_mov_b32_e32 v89, v50
	v_mov_b32_e32 v90, v50
	v_mov_b32_e32 v91, v50
	v_mov_b32_e32 v92, v50
	v_mov_b32_e32 v93, v50
	v_mov_b32_e32 v94, v50
	v_mov_b32_e32 v95, v50
	v_mov_b32_e32 v96, v50
	v_mov_b32_e32 v97, v50
	v_mov_b32_e32 v102, v50
	v_mov_b32_e32 v103, v50
	v_mov_b32_e32 v104, v50
	v_mov_b32_e32 v105, v50
	v_mov_b32_e32 v98, v50
	v_mov_b32_e32 v99, v50
	v_mov_b32_e32 v100, v50
	v_mov_b32_e32 v101, v50
	v_mov_b32_e32 v106, v50
	v_mov_b32_e32 v107, v50
	v_mov_b32_e32 v108, v50
	v_mov_b32_e32 v109, v50
	v_mov_b32_e32 v110, v50
	v_mov_b32_e32 v111, v50
	v_mov_b32_e32 v112, v50
	v_mov_b32_e32 v113, v50
	s_barrier
	s_waitcnt vmcnt(11)
	ds_write_b128 v141, v[26:29] offset:2304
	s_waitcnt vmcnt(9)
	ds_write_b128 v141, v[30:33] offset:10496
	s_waitcnt vmcnt(7)
	ds_write_b128 v141, v[34:37] offset:18688
	s_waitcnt vmcnt(5)
	ds_write_b128 v141, v[38:41] offset:26880
	s_waitcnt vmcnt(3)
	ds_write_b128 v141, v[42:45] offset:35072
	s_waitcnt vmcnt(1)
	ds_write_b128 v141, v[46:49] offset:43264
	s_waitcnt vmcnt(0)
	ds_write_b128 v141, v[14:17] offset:51456
	ds_write_b128 v141, v[18:21] offset:59648
	ds_write_b128 v146, v[22:25]
	ds_write_b128 v147, v[2:5]
	ds_write_b128 v148, v[6:9]
	ds_write_b128 v149, v[10:13]
	s_waitcnt lgkmcnt(0)
	s_barrier
.LBB0_1060:
	v_add_u32_e32 v0, v144, v142
	v_add_u32_e32 v132, v145, v142
	ds_read_b128 v[26:29], v0 offset:35072
	ds_read_b128 v[30:33], v0 offset:37120
	ds_read_b128 v[34:37], v132 offset:2304
	ds_read_b128 v[38:41], v132 offset:4352
	ds_read_b128 v[46:49], v0 offset:39168
	v_add_u32_e32 v133, v145, v143
	s_waitcnt lgkmcnt(2)
	v_mfma_f32_16x16x32_bf16 v[42:45], v[26:29], v[34:37], v[50:53]
	s_add_i32 s19, s18, 4
	s_min_u32 s19, s19, 15
	v_mfma_f32_16x16x32_bf16 v[50:53], v[30:33], v[34:37], v[54:57]
	s_nop 2
	ds_read_b128 v[54:57], v0 offset:41216
	s_waitcnt lgkmcnt(1)
	v_mfma_f32_16x16x32_bf16 v[58:61], v[46:49], v[34:37], v[58:61]
	v_add_u32_e32 v0, v144, v143
	s_waitcnt lgkmcnt(0)
	v_mfma_f32_16x16x32_bf16 v[34:37], v[54:57], v[34:37], v[62:65]
	v_mfma_f32_16x16x32_bf16 v[62:65], v[26:29], v[38:41], v[66:69]
	v_mfma_f32_16x16x32_bf16 v[66:69], v[30:33], v[38:41], v[70:73]
	v_mfma_f32_16x16x32_bf16 v[70:73], v[46:49], v[38:41], v[74:77]
	v_mfma_f32_16x16x32_bf16 v[38:41], v[54:57], v[38:41], v[78:81]
	s_nop 1
	ds_read_b128 v[74:77], v132 offset:6400
	ds_read_b128 v[78:81], v132 offset:8448
	ds_read_b128 v[18:21], v0 offset:35072
	ds_read_b128 v[22:25], v0 offset:37120
	s_waitcnt lgkmcnt(3)
	v_mfma_f32_16x16x32_bf16 v[82:85], v[26:29], v[74:77], v[82:85]
	v_mfma_f32_16x16x32_bf16 v[86:89], v[30:33], v[74:77], v[86:89]
	v_mfma_f32_16x16x32_bf16 v[90:93], v[46:49], v[74:77], v[90:93]
	v_mfma_f32_16x16x32_bf16 v[74:77], v[54:57], v[74:77], v[94:97]
	s_waitcnt lgkmcnt(2)
	v_mfma_f32_16x16x32_bf16 v[94:97], v[26:29], v[78:81], v[102:105]
	v_mfma_f32_16x16x32_bf16 v[98:101], v[30:33], v[78:81], v[98:101]
	ds_read_b128 v[26:29], v133 offset:2304
	ds_read_b128 v[30:33], v133 offset:4352
	ds_read_b128 v[102:105], v0 offset:39168
	ds_read_b128 v[136:139], v133 offset:8448
	v_mfma_f32_16x16x32_bf16 v[14:17], v[46:49], v[78:81], v[106:109]
	s_nop 2
	ds_read_b128 v[106:109], v0 offset:41216
	v_mfma_f32_16x16x32_bf16 v[54:57], v[54:57], v[78:81], v[110:113]
	v_lshl_or_b32 v0, s19, 7, v251
	v_lshl_add_u64 v[46:47], v[130:131], 0, v[0:1]
	s_add_i32 s19, s18, 2
	s_waitcnt lgkmcnt(4)
	v_mfma_f32_16x16x32_bf16 v[78:81], v[18:21], v[26:29], v[42:45]
	s_min_u32 s18, s19, 12
	s_cmp_lt_u32 s19, 14
	v_mfma_f32_16x16x32_bf16 v[50:53], v[22:25], v[26:29], v[50:53]
	v_lshl_add_u64 v[42:43], v[128:129], 0, v[0:1]
	s_waitcnt lgkmcnt(2)
	v_mfma_f32_16x16x32_bf16 v[58:61], v[102:105], v[26:29], v[58:61]
	s_waitcnt lgkmcnt(0)
	v_mfma_f32_16x16x32_bf16 v[110:113], v[106:109], v[26:29], v[34:37]
	ds_read_b128 v[26:29], v133 offset:6400
	v_lshl_add_u64 v[34:35], v[124:125], 0, v[0:1]
	v_mfma_f32_16x16x32_bf16 v[62:65], v[18:21], v[30:33], v[62:65]
	v_mfma_f32_16x16x32_bf16 v[66:69], v[22:25], v[30:33], v[66:69]
	v_mfma_f32_16x16x32_bf16 v[70:73], v[102:105], v[30:33], v[70:73]
	v_mfma_f32_16x16x32_bf16 v[114:117], v[106:109], v[30:33], v[38:41]
	v_lshl_add_u64 v[30:31], v[118:119], 0, v[0:1]
	v_lshl_add_u64 v[32:33], v[120:121], 0, v[0:1]
	s_waitcnt lgkmcnt(0)
	v_mfma_f32_16x16x32_bf16 v[82:85], v[18:21], v[26:29], v[82:85]
	v_lshl_add_u64 v[38:39], v[126:127], 0, v[0:1]
	v_lshl_or_b32 v0, s18, 7, v251
	s_mov_b32 s18, s19
	v_mfma_f32_16x16x32_bf16 v[2:5], v[22:25], v[26:29], v[86:89]
	v_mfma_f32_16x16x32_bf16 v[6:9], v[102:105], v[26:29], v[90:93]
	v_mfma_f32_16x16x32_bf16 v[10:13], v[106:109], v[26:29], v[74:77]
	s_waitcnt vmcnt(0) lgkmcnt(0)
	s_barrier
	ds_read_b128 v[74:77], v153
	ds_read_b128 v[86:89], v153 offset:2048
	v_mfma_f32_16x16x32_bf16 v[18:21], v[18:21], v[136:139], v[94:97]
	ds_read_b128 v[90:93], v132 offset:51456
	s_nop 1
	ds_read_b128 v[94:97], v132 offset:53504
	v_mfma_f32_16x16x32_bf16 v[22:25], v[22:25], v[136:139], v[98:101]
	v_mfma_f32_16x16x32_bf16 v[14:17], v[102:105], v[136:139], v[14:17]
	s_nop 1
	ds_read_b128 v[98:101], v153 offset:4096
	s_cmp_lt_u32 s19, 14
	s_cbranch_scc0 .Lffn_skip1
	s_mov_b32 m0, s98
	s_nop 0
	global_load_lds_dwordx4 v[30:31], off
	s_add_u32 m0, s98, 0x2000
	s_nop 0
	global_load_lds_dwordx4 v[32:33], off
	s_add_u32 m0, s98, 0x4000
	s_nop 0
	global_load_lds_dwordx4 v[34:35], off
	s_add_u32 m0, s98, 0x6000
	s_nop 0
	global_load_lds_dwordx4 v[38:39], off
	s_add_u32 m0, s98, 0x8000
	s_nop 0
	global_load_lds_dwordx4 v[42:43], off
	s_add_u32 m0, s98, 0xa000
	s_nop 0
	global_load_lds_dwordx4 v[46:47], off
; #define GLOAD(RA, RB, KT) do { const int kc_ = (KT) * 8 + lc; _Pragma("unroll") for (int j = 0; j < NA; ++j) RA[j] = al.load(j, kc_); _Pragma("unroll") for (int j = 0; j < NB; ++j) RB[j] = bl.load(j, kc_); } while (0)
; #define GLOAD(RA, RB, KT) do { const int kc_ = (KT) * 8 + lc; _Pragma("unroll") for (int j = 0; j < NA; ++j) RA[j] = al.load(j, kc_); _Pragma("unroll") for (int j = 0; j < NB; ++j) RB[j] = bl.load(j, kc_); } while (0)
; #define COMPUTE(BUF, RA, RB, WBUF) do { const char* sb = lds + (BUF) * STAGE; char* w_ = wa + (WBUF) * STAGE; \
;     KSTEP(o0); *(u32x4*)(w_) = RA[0]; *(u32x4*)(w_ + 64 * RB_) = RA[1]; *(u32x4*)(w_ + 128 * RB_) = RA[2]; \
;     KSTEP(o1); *(u32x4*)(w_ + 192 * RB_) = RA[3]; *(u32x4*)(w_ + AB) = RB[0]; *(u32x4*)(w_ + AB + 64 * RB_) = RB[1]; } while (0)
; template <bool SW, class AL, class BL>
; DI void gemm_run16(int tid, char* lds, const AL& al, const BL& bl, int nk, f32x4 (&acc)[4][4], u32x4 (&ra0)[4], u32x4 (&rb0)[2], u32x4 (&ra1)[4], u32x4 (&rb1)[2]) {
;     ...
;   for (int kt = 0; kt < nk; kt += 2) {
;     GLOAD(ra0, rb0, (kt + 2 < kl ? kt + 2 : kl));
;     COMPUTE(0, ra1, rb1, 1);
;     __syncthreads();
;     if (kt + 1 >= nk) break;
;     GLOAD(ra1, rb1, (kt + 3 < kl ? kt + 3 : kl));
;     COMPUTE(1, ra0, rb0, 0);
;     __syncthreads();
.Lffn_skip1:
	s_waitcnt lgkmcnt(2)
	v_mfma_f32_16x16x32_bf16 v[102:105], v[86:89], v[90:93], v[50:53]
	s_nop 2
	ds_read_b128 v[50:53], v153 offset:6144
	v_mfma_f32_16x16x32_bf16 v[54:57], v[106:109], v[136:139], v[54:57]
	v_mfma_f32_16x16x32_bf16 v[78:81], v[74:77], v[90:93], v[78:81]
	s_waitcnt lgkmcnt(1)
	v_mfma_f32_16x16x32_bf16 v[58:61], v[98:101], v[90:93], v[58:61]
	s_waitcnt lgkmcnt(0)
	v_mfma_f32_16x16x32_bf16 v[90:93], v[50:53], v[90:93], v[110:113]
	v_mfma_f32_16x16x32_bf16 v[106:109], v[74:77], v[94:97], v[62:65]
	v_mfma_f32_16x16x32_bf16 v[110:113], v[86:89], v[94:97], v[66:69]
	s_nop 1
	ds_read_b128 v[62:65], v132 offset:55552
	ds_read_b128 v[66:69], v132 offset:57600
	v_mfma_f32_16x16x32_bf16 v[136:139], v[98:101], v[94:97], v[70:73]
	v_mfma_f32_16x16x32_bf16 v[94:97], v[50:53], v[94:97], v[114:117]
	s_waitcnt lgkmcnt(1)
	v_mfma_f32_16x16x32_bf16 v[6:9], v[98:101], v[62:65], v[6:9]
	s_waitcnt lgkmcnt(0)
	v_mfma_f32_16x16x32_bf16 v[114:117], v[74:77], v[66:69], v[18:21]
	v_mfma_f32_16x16x32_bf16 v[158:161], v[86:89], v[66:69], v[22:25]
	v_mfma_f32_16x16x32_bf16 v[162:165], v[98:101], v[66:69], v[14:17]
	s_nop 1
	ds_read_b128 v[22:25], v154
	ds_read_b128 v[98:101], v154 offset:2048
	ds_read_b128 v[14:17], v133 offset:51456
	ds_read_b128 v[18:21], v133 offset:53504
	ds_read_b128 v[170:173], v154 offset:4096
	ds_read_b128 v[174:177], v154 offset:6144
	v_mfma_f32_16x16x32_bf16 v[82:85], v[74:77], v[62:65], v[82:85]
	v_mfma_f32_16x16x32_bf16 v[2:5], v[86:89], v[62:65], v[2:5]
	v_mfma_f32_16x16x32_bf16 v[10:13], v[50:53], v[62:65], v[10:13]
	v_mfma_f32_16x16x32_bf16 v[166:169], v[50:53], v[66:69], v[54:57]
	s_waitcnt lgkmcnt(3)
	v_mfma_f32_16x16x32_bf16 v[50:53], v[22:25], v[14:17], v[78:81]
	v_mfma_f32_16x16x32_bf16 v[54:57], v[98:101], v[14:17], v[102:105]
	s_waitcnt lgkmcnt(1)
	v_mfma_f32_16x16x32_bf16 v[58:61], v[170:173], v[14:17], v[58:61]
	s_waitcnt lgkmcnt(0)
	v_mfma_f32_16x16x32_bf16 v[62:65], v[174:177], v[14:17], v[90:93]
	v_mfma_f32_16x16x32_bf16 v[70:73], v[98:101], v[18:21], v[110:113]
	ds_read_b128 v[14:17], v133 offset:55552
	s_nop 1
	ds_read_b128 v[110:113], v133 offset:57600
	s_waitcnt lgkmcnt(1)
	v_mfma_f32_16x16x32_bf16 v[86:89], v[98:101], v[14:17], v[2:5]
	s_nop 2
	v_lshl_add_u64 v[2:3], v[118:119], 0, v[0:1]
	v_lshl_add_u64 v[4:5], v[120:121], 0, v[0:1]
	v_mfma_f32_16x16x32_bf16 v[90:93], v[170:173], v[14:17], v[6:9]
	s_nop 2
	v_lshl_add_u64 v[6:7], v[124:125], 0, v[0:1]
	v_lshl_add_u64 v[8:9], v[126:127], 0, v[0:1]
	v_mfma_f32_16x16x32_bf16 v[66:69], v[22:25], v[18:21], v[106:109]
	v_mfma_f32_16x16x32_bf16 v[74:77], v[170:173], v[18:21], v[136:139]
	s_nop 1
	v_lshl_add_u64 v[106:107], v[128:129], 0, v[0:1]
	v_mfma_f32_16x16x32_bf16 v[78:81], v[174:177], v[18:21], v[94:97]
	v_mfma_f32_16x16x32_bf16 v[82:85], v[22:25], v[14:17], v[82:85]
	v_mfma_f32_16x16x32_bf16 v[94:97], v[174:177], v[14:17], v[10:13]
	s_waitcnt lgkmcnt(0)
	v_mfma_f32_16x16x32_bf16 v[102:105], v[22:25], v[110:113], v[114:117]
	v_mfma_f32_16x16x32_bf16 v[98:101], v[98:101], v[110:113], v[158:161]
	s_nop 0
	v_lshl_add_u64 v[10:11], v[130:131], 0, v[0:1]
	s_waitcnt vmcnt(0) lgkmcnt(0)
	s_barrier
	s_cmp_lt_u32 s19, 14
	s_cbranch_scc0 .Lffn_skip2
	s_add_u32 m0, s98, 0xbe80
	s_nop 0
	global_load_lds_dwordx4 v[2:3], off offset:384
	s_add_u32 m0, s98, 0xde80
	s_nop 0
	global_load_lds_dwordx4 v[4:5], off offset:384
	s_add_u32 m0, s98, 0xfe80
	s_nop 0
	global_load_lds_dwordx4 v[6:7], off offset:384
	s_add_u32 m0, s98, 0x11e80
	s_nop 0
	global_load_lds_dwordx4 v[8:9], off offset:384
	s_add_u32 m0, s98, 0x13e80
	s_nop 0
	global_load_lds_dwordx4 v[106:107], off offset:384
	s_add_u32 m0, s98, 0x15e80
	s_nop 0
	global_load_lds_dwordx4 v[10:11], off offset:384
.Lffn_skip2:
	v_mfma_f32_16x16x32_bf16 v[106:109], v[170:173], v[110:113], v[162:165]
	v_mfma_f32_16x16x32_bf16 v[110:113], v[174:177], v[110:113], v[166:169]
	s_cmp_lt_u32 s19, 14
	s_cbranch_scc1 .LBB0_1060
	s_add_i32 s20, s29, 1
	s_cmp_ge_i32 s20, s28
	s_cbranch_scc1 .LBB0_1072
	s_lshl_b32 s18, s29, 3
	v_readlane_b32 s14, v254, 25
	s_add_i32 s37, s14, s18
	s_mul_i32 s18, s66, s20
	s_add_i32 s21, s94, s18
	s_mov_b32 s31, 0
	s_mov_b32 s33, 0
	s_branch .LBB0_1064

; __global__ void __launch_bounds__(NTHREADS) fwd_kernel(P p) {
	.amdhsa_kernel _Z10fwd_kernel1P
		.amdhsa_group_segment_fixed_size 0
		.amdhsa_private_segment_fixed_size 0
		.amdhsa_kernarg_size 536
		.amdhsa_user_sgpr_count 2
		.amdhsa_user_sgpr_dispatch_ptr 0
		.amdhsa_user_sgpr_queue_ptr 0
		.amdhsa_user_sgpr_kernarg_segment_ptr 1
		.amdhsa_user_sgpr_dispatch_id 0
		.amdhsa_user_sgpr_kernarg_preload_length 0
		.amdhsa_user_sgpr_kernarg_preload_offset 0
		.amdhsa_user_sgpr_private_segment_size 0
		.amdhsa_uses_dynamic_stack 0
		.amdhsa_enable_private_segment 0
		.amdhsa_system_sgpr_workgroup_id_x 1
		.amdhsa_system_sgpr_workgroup_id_y 0
		.amdhsa_system_sgpr_workgroup_id_z 0
		.amdhsa_system_sgpr_workgroup_info 0
		.amdhsa_system_vgpr_workitem_id 2
		.amdhsa_next_free_vgpr 256
		.amdhsa_next_free_sgpr 100
		.amdhsa_accum_offset 256
		.amdhsa_reserve_vcc 1
		.amdhsa_float_round_mode_32 0
		.amdhsa_float_round_mode_16_64 0
		.amdhsa_float_denorm_mode_32 3
		.amdhsa_float_denorm_mode_16_64 3
		.amdhsa_dx10_clamp 1
		.amdhsa_ieee_mode 1
		.amdhsa_fp16_overflow 0
		.amdhsa_tg_split 0
		.amdhsa_exception_fp_ieee_invalid_op 0
		.amdhsa_exception_fp_denorm_src 0
		.amdhsa_exception_fp_ieee_div_zero 0
		.amdhsa_exception_fp_ieee_overflow 0
		.amdhsa_exception_fp_ieee_underflow 0
		.amdhsa_exception_fp_ieee_inexact 0
		.amdhsa_exception_int_div_zero 0
	.end_amdhsa_kernel

; __global__ void __launch_bounds__(NTHREADS) fwd_kernel(P p) {
amdhsa.kernels:
  - .agpr_count:     0
    .args:
      - .offset:         0
        .size:           280
        .value_kind:     by_value
      - .offset:         280
        .size:           4
        .value_kind:     hidden_block_count_x
      - .offset:         284
        .size:           4
        .value_kind:     hidden_block_count_y
      - .offset:         288
        .size:           4
        .value_kind:     hidden_block_count_z
      - .offset:         292
        .size:           2
        .value_kind:     hidden_group_size_x
      - .offset:         294
        .size:           2
        .value_kind:     hidden_group_size_y
      - .offset:         296
        .size:           2
        .value_kind:     hidden_group_size_z
      - .offset:         298
        .size:           2
        .value_kind:     hidden_remainder_x
      - .offset:         300
        .size:           2
        .value_kind:     hidden_remainder_y
      - .offset:         302
        .size:           2
        .value_kind:     hidden_remainder_z
      - .offset:         320
        .size:           8
        .value_kind:     hidden_global_offset_x
      - .offset:         328
        .size:           8
        .value_kind:     hidden_global_offset_y
      - .offset:         336
        .size:           8
        .value_kind:     hidden_global_offset_z
      - .offset:         344
        .size:           2
        .value_kind:     hidden_grid_dims
      - .offset:         368
        .size:           8
        .value_kind:     hidden_multigrid_sync_arg
      - .offset:         400
        .size:           4
        .value_kind:     hidden_dynamic_lds_size
    .group_segment_fixed_size: 0
    .kernarg_segment_align: 8
    .kernarg_segment_size: 536
    .language:       OpenCL C
    .language_version:
      - 2
      - 0
    .max_flat_workgroup_size: 512
    .name:           _Z10fwd_kernel1P
    .private_segment_fixed_size: 0
    .sgpr_count:     106
    .sgpr_spill_count: 229
    .symbol:         _Z10fwd_kernel1P.kd
    .uniform_work_group_size: 1
    .uses_dynamic_stack: false
    .vgpr_count:     256
    .vgpr_spill_count: 0
    .wavefront_size: 64
